# v105 + non-temporal output stores for the QK/K-image/Vt projections (GEMM0, GEMM1) and the SwiGLU output F: the streamed outputs no longer evict the GEMM operands from the caches
# speedup vs baseline: 1.0031x; 1.0031x over previous
; __device__ __forceinline__ unsigned cvtpk(float lo, float hi) { f32x2_t v = {lo, hi}; bf16x2_t b = __builtin_convertvector(v, bf16x2_t); return __builtin_bit_cast(unsigned, b); }
; #define PG8_BAR __builtin_amdgcn_s_barrier()
; template <int mode>
; __device__ __forceinline__ void epilogue(f32x4 (&acc)[2][2][4][2], const GUnit& u, int wr, int wc, int fr, int fq, LAS unsigned char* lds) {
;     if (mode == 0) {
;         bf16_t* base = (bf16_t*)u.C; const float sc = u.scale;
; #pragma unroll
;         for (int ai = 0; ai < 2; ++ai)
; #pragma unroll
;             for (int m = 0; m < 4; ++m) {
;                 bf16_t* rowp = base + (size_t)ai * u.SA + (size_t)(wr * 64 + m * 16 + fr) * u.SR + (wc >> 1) * u.SX + (wc & 1) * 32 + 8 * fq;
; #pragma unroll
;                 for (int bj = 0; bj < 2; ++bj) {
;                     const f32x4 v0 = acc[ai][bj][m][0] * sc, v1 = acc[ai][bj][m][1] * sc;
;                     u32x4 w; w.x = cvtpk(v0[0], v0[1]); w.y = cvtpk(v0[2], v0[3]); w.z = cvtpk(v1[0], v1[1]); w.w = cvtpk(v1[2], v1[3]);
;                     *(u32x4*)(rowp + (size_t)bj * u.SB) = w;
;                 }
;             }
; template <int GI>
; __device__ __forceinline__ void gemm_phase(LAS unsigned char* lds, unsigned char* ws, int G, int cblk) {
;     ...
;         if (wr == 0) PG8_BAR;
;         epilogue<g.mode>(acc, cur, wr, wc, fr, fq, lds);
;         if (!has_next) break;
; #pragma unroll
;         for (int a = 0; a < 2; ++a)
; #pragma unroll
;             for (int b = 0; b < 2; ++b)
; #pragma unroll
;                 for (int m = 0; m < 4; ++m)
; #pragma unroll
;                     for (int n = 0; n < 2; ++n) acc[a][b][m][n] = (f32x4){0.f, 0.f, 0.f, 0.f};
;         cur = nxt; cA = nA; cB = nB; ++ui;
;         if (wr == 1) PG8_BAR;
.LBB0_101:
	v_mul_lo_u32 v161, s69, v138
	v_mul_lo_u32 v164, s68, v139
	v_mad_u64_u32 v[158:159], s[4:5], s68, v138, 0
	v_add3_u32 v159, v159, v164, v161
	v_lshlrev_b64 v[158:159], 1, v[158:159]
	s_mul_i32 s58, s77, s26
	v_lshl_add_u64 v[164:165], s[12:13], 0, v[158:159]
	s_lshl_b64 s[4:5], s[58:59], 1
	v_lshl_add_u64 v[164:165], v[164:165], 0, s[4:5]
	s_mov_b32 s77, s59
	v_lshl_add_u64 v[164:165], v[164:165], 0, s[76:77]
	v_pk_mul_f32 v[126:127], v[146:147], v[126:127] op_sel_hi:[0,1]
	v_pk_mul_f32 v[124:125], v[146:147], v[124:125] op_sel_hi:[0,1]
	v_pk_mul_f32 v[166:167], v[146:147], v[122:123] op_sel_hi:[0,1]
	v_pk_mul_f32 v[122:123], v[146:147], v[120:121] op_sel_hi:[0,1]
	v_lshl_add_u64 v[164:165], v[164:165], 0, v[136:137]
	v_cvt_pk_bf16_f32 v120, v124, v125
	v_cvt_pk_bf16_f32 v121, v126, v127
	v_cvt_pk_bf16_f32 v122, v122, v123
	v_cvt_pk_bf16_f32 v123, v166, v167
	global_store_dwordx4 v[164:165], v[120:123], off nt
	v_pk_mul_f32 v[118:119], v[146:147], v[118:119] op_sel_hi:[0,1]
	v_pk_mul_f32 v[116:117], v[146:147], v[116:117] op_sel_hi:[0,1]
	v_pk_mul_f32 v[120:121], v[146:147], v[110:111] op_sel_hi:[0,1]
	v_pk_mul_f32 v[110:111], v[146:147], v[108:109] op_sel_hi:[0,1]
	s_lshl_b64 s[6:7], s[74:75], 1
	v_cvt_pk_bf16_f32 v108, v116, v117
	v_cvt_pk_bf16_f32 v109, v118, v119
	v_cvt_pk_bf16_f32 v110, v110, v111
	v_cvt_pk_bf16_f32 v111, v120, v121
	v_lshl_add_u64 v[116:117], v[164:165], 0, s[6:7]
	global_store_dwordx4 v[116:117], v[108:111], off nt
	v_pk_mul_f32 v[114:115], v[146:147], v[114:115] op_sel_hi:[0,1]
	v_pk_mul_f32 v[112:113], v[146:147], v[112:113] op_sel_hi:[0,1]
	v_mul_lo_u32 v110, s69, v140
	v_mul_lo_u32 v111, s68, v141
	v_mad_u64_u32 v[108:109], s[74:75], s68, v140, 0
	v_add3_u32 v109, v109, v111, v110
	v_lshlrev_b64 v[108:109], 1, v[108:109]
	v_lshl_add_u64 v[110:111], s[12:13], 0, v[108:109]
	v_lshl_add_u64 v[110:111], v[110:111], 0, s[4:5]
	v_lshl_add_u64 v[110:111], v[110:111], 0, s[76:77]
	v_pk_mul_f32 v[116:117], v[146:147], v[106:107] op_sel_hi:[0,1]
	v_pk_mul_f32 v[106:107], v[146:147], v[104:105] op_sel_hi:[0,1]
	v_lshl_add_u64 v[110:111], v[110:111], 0, v[136:137]
	v_cvt_pk_bf16_f32 v104, v112, v113
	v_cvt_pk_bf16_f32 v105, v114, v115
	v_cvt_pk_bf16_f32 v106, v106, v107
	v_cvt_pk_bf16_f32 v107, v116, v117
	global_store_dwordx4 v[110:111], v[104:107], off nt
	v_pk_mul_f32 v[102:103], v[146:147], v[102:103] op_sel_hi:[0,1]
	v_pk_mul_f32 v[100:101], v[146:147], v[100:101] op_sel_hi:[0,1]
	v_pk_mul_f32 v[104:105], v[146:147], v[94:95] op_sel_hi:[0,1]
	v_pk_mul_f32 v[94:95], v[146:147], v[92:93] op_sel_hi:[0,1]
	v_cvt_pk_bf16_f32 v92, v100, v101
	v_cvt_pk_bf16_f32 v93, v102, v103
	v_cvt_pk_bf16_f32 v94, v94, v95
	v_cvt_pk_bf16_f32 v95, v104, v105
	v_lshl_add_u64 v[100:101], v[110:111], 0, s[6:7]
	global_store_dwordx4 v[100:101], v[92:95], off nt
	v_pk_mul_f32 v[98:99], v[146:147], v[98:99] op_sel_hi:[0,1]
	v_pk_mul_f32 v[96:97], v[146:147], v[96:97] op_sel_hi:[0,1]
	v_mul_lo_u32 v94, s69, v142
	v_mul_lo_u32 v95, s68, v143
	v_mad_u64_u32 v[92:93], s[74:75], s68, v142, 0
	v_add3_u32 v93, v93, v95, v94
	v_lshlrev_b64 v[92:93], 1, v[92:93]
	v_lshl_add_u64 v[94:95], s[12:13], 0, v[92:93]
	v_lshl_add_u64 v[94:95], v[94:95], 0, s[4:5]
	v_lshl_add_u64 v[94:95], v[94:95], 0, s[76:77]
	v_pk_mul_f32 v[100:101], v[146:147], v[90:91] op_sel_hi:[0,1]
	v_pk_mul_f32 v[90:91], v[146:147], v[88:89] op_sel_hi:[0,1]
	v_lshl_add_u64 v[94:95], v[94:95], 0, v[136:137]
	v_cvt_pk_bf16_f32 v88, v96, v97
	v_cvt_pk_bf16_f32 v89, v98, v99
	v_cvt_pk_bf16_f32 v90, v90, v91
	v_cvt_pk_bf16_f32 v91, v100, v101
	global_store_dwordx4 v[94:95], v[88:91], off nt
	v_pk_mul_f32 v[86:87], v[146:147], v[86:87] op_sel_hi:[0,1]
	v_pk_mul_f32 v[84:85], v[146:147], v[84:85] op_sel_hi:[0,1]
	v_pk_mul_f32 v[88:89], v[146:147], v[78:79] op_sel_hi:[0,1]
	v_pk_mul_f32 v[78:79], v[146:147], v[76:77] op_sel_hi:[0,1]
	v_cvt_pk_bf16_f32 v76, v84, v85
	v_cvt_pk_bf16_f32 v77, v86, v87
	v_cvt_pk_bf16_f32 v78, v78, v79
	v_cvt_pk_bf16_f32 v79, v88, v89
	v_lshl_add_u64 v[84:85], v[94:95], 0, s[6:7]
	global_store_dwordx4 v[84:85], v[76:79], off nt
	v_pk_mul_f32 v[82:83], v[146:147], v[82:83] op_sel_hi:[0,1]
	v_pk_mul_f32 v[80:81], v[146:147], v[80:81] op_sel_hi:[0,1]
	v_mul_lo_u32 v78, s69, v144
	v_mul_lo_u32 v79, s68, v145
	v_mad_u64_u32 v[76:77], s[68:69], s68, v144, 0
	v_add3_u32 v77, v77, v79, v78
	v_lshlrev_b64 v[76:77], 1, v[76:77]
	v_lshl_add_u64 v[78:79], s[12:13], 0, v[76:77]
	v_lshl_add_u64 v[78:79], v[78:79], 0, s[4:5]
	v_lshl_add_u64 v[78:79], v[78:79], 0, s[76:77]
	v_pk_mul_f32 v[84:85], v[146:147], v[74:75] op_sel_hi:[0,1]
	v_pk_mul_f32 v[74:75], v[146:147], v[72:73] op_sel_hi:[0,1]
	v_lshl_add_u64 v[78:79], v[78:79], 0, v[136:137]
	v_cvt_pk_bf16_f32 v72, v80, v81
	v_cvt_pk_bf16_f32 v73, v82, v83
	v_cvt_pk_bf16_f32 v74, v74, v75
	v_cvt_pk_bf16_f32 v75, v84, v85
	s_lshl_b64 s[38:39], s[38:39], 1
	global_store_dwordx4 v[78:79], v[72:75], off nt
	v_pk_mul_f32 v[70:71], v[146:147], v[70:71] op_sel_hi:[0,1]
; __device__ __forceinline__ unsigned cvtpk(float lo, float hi) { f32x2_t v = {lo, hi}; bf16x2_t b = __builtin_convertvector(v, bf16x2_t); return __builtin_bit_cast(unsigned, b); }
; #define PG8_BAR __builtin_amdgcn_s_barrier()
; template <int mode>
; __device__ __forceinline__ void epilogue(f32x4 (&acc)[2][2][4][2], const GUnit& u, int wr, int wc, int fr, int fq, LAS unsigned char* lds) {
;     if (mode == 0) {
;         bf16_t* base = (bf16_t*)u.C; const float sc = u.scale;
; #pragma unroll
;         for (int ai = 0; ai < 2; ++ai)
; #pragma unroll
;             for (int m = 0; m < 4; ++m) {
;                 bf16_t* rowp = base + (size_t)ai * u.SA + (size_t)(wr * 64 + m * 16 + fr) * u.SR + (wc >> 1) * u.SX + (wc & 1) * 32 + 8 * fq;
; #pragma unroll
;                 for (int bj = 0; bj < 2; ++bj) {
;                     const f32x4 v0 = acc[ai][bj][m][0] * sc, v1 = acc[ai][bj][m][1] * sc;
;                     u32x4 w; w.x = cvtpk(v0[0], v0[1]); w.y = cvtpk(v0[2], v0[3]); w.z = cvtpk(v1[0], v1[1]); w.w = cvtpk(v1[2], v1[3]);
;                     *(u32x4*)(rowp + (size_t)bj * u.SB) = w;
;                 }
;             }
; template <int GI>
; __device__ __forceinline__ void gemm_phase(LAS unsigned char* lds, unsigned char* ws, int G, int cblk) {
;     ...
;         if (wr == 0) PG8_BAR;
;         epilogue<g.mode>(acc, cur, wr, wc, fr, fq, lds);
;         if (!has_next) break;
; #pragma unroll
;         for (int a = 0; a < 2; ++a)
; #pragma unroll
;             for (int b = 0; b < 2; ++b)
; #pragma unroll
;                 for (int m = 0; m < 4; ++m)
; #pragma unroll
;                     for (int n = 0; n < 2; ++n) acc[a][b][m][n] = (f32x4){0.f, 0.f, 0.f, 0.f};
;         cur = nxt; cA = nA; cB = nB; ++ui;
;         if (wr == 1) PG8_BAR;
	v_pk_mul_f32 v[68:69], v[146:147], v[68:69] op_sel_hi:[0,1]
	v_pk_mul_f32 v[72:73], v[146:147], v[66:67] op_sel_hi:[0,1]
	v_pk_mul_f32 v[66:67], v[146:147], v[64:65] op_sel_hi:[0,1]
	s_add_u32 s12, s12, s38
	v_cvt_pk_bf16_f32 v64, v68, v69
	v_cvt_pk_bf16_f32 v65, v70, v71
	v_cvt_pk_bf16_f32 v66, v66, v67
	v_cvt_pk_bf16_f32 v67, v72, v73
	v_lshl_add_u64 v[68:69], v[78:79], 0, s[6:7]
	s_addc_u32 s13, s13, s39
	global_store_dwordx4 v[68:69], v[64:67], off nt
	v_pk_mul_f32 v[62:63], v[146:147], v[62:63] op_sel_hi:[0,1]
	v_pk_mul_f32 v[60:61], v[146:147], v[60:61] op_sel_hi:[0,1]
	v_lshl_add_u64 v[64:65], s[12:13], 0, v[158:159]
	v_lshl_add_u64 v[64:65], v[64:65], 0, s[4:5]
	v_lshl_add_u64 v[64:65], v[64:65], 0, s[76:77]
	v_pk_mul_f32 v[66:67], v[146:147], v[58:59] op_sel_hi:[0,1]
	v_pk_mul_f32 v[58:59], v[146:147], v[56:57] op_sel_hi:[0,1]
	v_lshl_add_u64 v[64:65], v[64:65], 0, v[136:137]
	v_cvt_pk_bf16_f32 v56, v60, v61
	v_cvt_pk_bf16_f32 v57, v62, v63
	v_cvt_pk_bf16_f32 v58, v58, v59
	v_cvt_pk_bf16_f32 v59, v66, v67
	global_store_dwordx4 v[64:65], v[56:59], off nt
	v_pk_mul_f32 v[50:51], v[146:147], v[50:51] op_sel_hi:[0,1]
	v_pk_mul_f32 v[48:49], v[146:147], v[48:49] op_sel_hi:[0,1]
	v_pk_mul_f32 v[56:57], v[146:147], v[42:43] op_sel_hi:[0,1]
	v_pk_mul_f32 v[42:43], v[146:147], v[40:41] op_sel_hi:[0,1]
	v_cvt_pk_bf16_f32 v40, v48, v49
	v_cvt_pk_bf16_f32 v41, v50, v51
	v_cvt_pk_bf16_f32 v42, v42, v43
	v_cvt_pk_bf16_f32 v43, v56, v57
	v_lshl_add_u64 v[48:49], v[64:65], 0, s[6:7]
	global_store_dwordx4 v[48:49], v[40:43], off nt
	v_pk_mul_f32 v[46:47], v[146:147], v[46:47] op_sel_hi:[0,1]
	v_pk_mul_f32 v[44:45], v[146:147], v[44:45] op_sel_hi:[0,1]
	v_lshl_add_u64 v[40:41], s[12:13], 0, v[108:109]
	v_lshl_add_u64 v[40:41], v[40:41], 0, s[4:5]
	v_lshl_add_u64 v[40:41], v[40:41], 0, s[76:77]
	v_lshl_add_u64 v[48:49], v[40:41], 0, v[136:137]
	v_pk_mul_f32 v[42:43], v[146:147], v[54:55] op_sel_hi:[0,1]
	v_pk_mul_f32 v[40:41], v[146:147], v[52:53] op_sel_hi:[0,1]
	v_cvt_pk_bf16_f32 v40, v40, v41
	v_cvt_pk_bf16_f32 v41, v42, v43
	v_cvt_pk_bf16_f32 v42, v44, v45
	v_cvt_pk_bf16_f32 v43, v46, v47
	global_store_dwordx4 v[48:49], v[40:43], off nt
	v_pk_mul_f32 v[34:35], v[146:147], v[34:35] op_sel_hi:[0,1]
	v_pk_mul_f32 v[32:33], v[146:147], v[32:33] op_sel_hi:[0,1]
	v_pk_mul_f32 v[40:41], v[146:147], v[26:27] op_sel_hi:[0,1]
	v_pk_mul_f32 v[26:27], v[146:147], v[24:25] op_sel_hi:[0,1]
	v_cvt_pk_bf16_f32 v24, v32, v33
	v_cvt_pk_bf16_f32 v25, v34, v35
	v_cvt_pk_bf16_f32 v26, v26, v27
	v_cvt_pk_bf16_f32 v27, v40, v41
	v_lshl_add_u64 v[32:33], v[48:49], 0, s[6:7]
	global_store_dwordx4 v[32:33], v[24:27], off nt
	v_pk_mul_f32 v[30:31], v[146:147], v[30:31] op_sel_hi:[0,1]
	v_pk_mul_f32 v[28:29], v[146:147], v[28:29] op_sel_hi:[0,1]
	v_lshl_add_u64 v[24:25], s[12:13], 0, v[92:93]
	v_lshl_add_u64 v[24:25], v[24:25], 0, s[4:5]
	v_lshl_add_u64 v[24:25], v[24:25], 0, s[76:77]
	v_lshl_add_u64 v[32:33], v[24:25], 0, v[136:137]
	v_pk_mul_f32 v[26:27], v[146:147], v[38:39] op_sel_hi:[0,1]
	v_pk_mul_f32 v[24:25], v[146:147], v[36:37] op_sel_hi:[0,1]
	v_cvt_pk_bf16_f32 v24, v24, v25
	v_cvt_pk_bf16_f32 v25, v26, v27
	v_cvt_pk_bf16_f32 v26, v28, v29
	v_cvt_pk_bf16_f32 v27, v30, v31
	global_store_dwordx4 v[32:33], v[24:27], off nt
	v_pk_mul_f32 v[18:19], v[146:147], v[18:19] op_sel_hi:[0,1]
	v_pk_mul_f32 v[16:17], v[146:147], v[16:17] op_sel_hi:[0,1]
	v_pk_mul_f32 v[24:25], v[146:147], v[10:11] op_sel_hi:[0,1]
	v_pk_mul_f32 v[10:11], v[146:147], v[8:9] op_sel_hi:[0,1]
	v_cvt_pk_bf16_f32 v8, v16, v17
	v_cvt_pk_bf16_f32 v9, v18, v19
	v_cvt_pk_bf16_f32 v10, v10, v11
	v_cvt_pk_bf16_f32 v11, v24, v25
	v_lshl_add_u64 v[16:17], v[32:33], 0, s[6:7]
	global_store_dwordx4 v[16:17], v[8:11], off nt
	v_pk_mul_f32 v[14:15], v[146:147], v[14:15] op_sel_hi:[0,1]
	v_pk_mul_f32 v[12:13], v[146:147], v[12:13] op_sel_hi:[0,1]
	v_lshl_add_u64 v[8:9], s[12:13], 0, v[76:77]
	v_lshl_add_u64 v[8:9], v[8:9], 0, s[4:5]
	v_lshl_add_u64 v[8:9], v[8:9], 0, s[76:77]
	v_lshl_add_u64 v[16:17], v[8:9], 0, v[136:137]
	v_pk_mul_f32 v[10:11], v[146:147], v[22:23] op_sel_hi:[0,1]
	v_pk_mul_f32 v[8:9], v[146:147], v[20:21] op_sel_hi:[0,1]
	v_cvt_pk_bf16_f32 v8, v8, v9
	v_cvt_pk_bf16_f32 v9, v10, v11
	v_cvt_pk_bf16_f32 v10, v12, v13
	v_cvt_pk_bf16_f32 v11, v14, v15
	global_store_dwordx4 v[16:17], v[8:11], off nt
	v_pk_mul_f32 v[6:7], v[146:147], v[6:7] op_sel_hi:[0,1]
	v_pk_mul_f32 v[4:5], v[146:147], v[4:5] op_sel_hi:[0,1]
	v_pk_mul_f32 v[8:9], v[146:147], v[2:3] op_sel_hi:[0,1]
	v_pk_mul_f32 v[2:3], v[146:147], v[0:1] op_sel_hi:[0,1]
	v_cvt_pk_bf16_f32 v0, v4, v5
	v_cvt_pk_bf16_f32 v1, v6, v7
	v_cvt_pk_bf16_f32 v2, v2, v3
	v_cvt_pk_bf16_f32 v3, v8, v9
	v_lshl_add_u64 v[4:5], v[16:17], 0, s[6:7]
	s_andn2_b64 vcc, exec, s[78:79]
	s_mov_b64 s[4:5], -1
	global_store_dwordx4 v[4:5], v[0:3], off nt
	s_cbranch_vccnz .LBB0_84
	s_andn2_b64 vcc, exec, s[62:63]
	s_cbranch_vccnz .LBB0_83
	s_barrier
	s_branch .LBB0_83

; __device__ __forceinline__ unsigned cvtpk(float lo, float hi) { f32x2_t v = {lo, hi}; bf16x2_t b = __builtin_convertvector(v, bf16x2_t); return __builtin_bit_cast(unsigned, b); }
; #define PG8_BAR __builtin_amdgcn_s_barrier()
; template <int mode>
; __device__ __forceinline__ void epilogue(f32x4 (&acc)[2][2][4][2], const GUnit& u, int wr, int wc, int fr, int fq, LAS unsigned char* lds) {
;     if (mode == 0) {
;         bf16_t* base = (bf16_t*)u.C; const float sc = u.scale;
; #pragma unroll
;         for (int ai = 0; ai < 2; ++ai)
; #pragma unroll
;             for (int m = 0; m < 4; ++m) {
;                 bf16_t* rowp = base + (size_t)ai * u.SA + (size_t)(wr * 64 + m * 16 + fr) * u.SR + (wc >> 1) * u.SX + (wc & 1) * 32 + 8 * fq;
; #pragma unroll
;                 for (int bj = 0; bj < 2; ++bj) {
;                     const f32x4 v0 = acc[ai][bj][m][0] * sc, v1 = acc[ai][bj][m][1] * sc;
;                     u32x4 w; w.x = cvtpk(v0[0], v0[1]); w.y = cvtpk(v0[2], v0[3]); w.z = cvtpk(v1[0], v1[1]); w.w = cvtpk(v1[2], v1[3]);
;                     *(u32x4*)(rowp + (size_t)bj * u.SB) = w;
;                 }
;             }
; template <int GI>
; __device__ __forceinline__ void gemm_phase(LAS unsigned char* lds, unsigned char* ws, int G, int cblk) {
;     ...
;         if (wr == 0) PG8_BAR;
;         epilogue<g.mode>(acc, cur, wr, wc, fr, fq, lds);
;         if (!has_next) break;
; #pragma unroll
;         for (int a = 0; a < 2; ++a)
; #pragma unroll
;             for (int b = 0; b < 2; ++b)
; #pragma unroll
;                 for (int m = 0; m < 4; ++m)
; #pragma unroll
;                     for (int n = 0; n < 2; ++n) acc[a][b][m][n] = (f32x4){0.f, 0.f, 0.f, 0.f};
;         cur = nxt; cA = nA; cB = nB; ++ui;
;         if (wr == 1) PG8_BAR;
.LBB0_127:
	v_mul_lo_u32 v156, s83, v138
	v_mul_lo_u32 v157, s82, v139
	v_mad_u64_u32 v[154:155], s[14:15], s82, v138, 0
	v_add3_u32 v155, v155, v157, v156
	v_lshlrev_b64 v[154:155], 1, v[154:155]
	s_mul_i32 s4, s33, s24
	v_lshl_add_u64 v[156:157], s[68:69], 0, v[154:155]
	s_lshl_b64 s[86:87], s[4:5], 1
	v_lshl_add_u64 v[156:157], v[156:157], 0, s[86:87]
	s_mov_b32 s63, s5
	v_lshl_add_u64 v[156:157], v[156:157], 0, s[62:63]
	v_lshl_add_u64 v[156:157], v[156:157], 0, v[136:137]
	s_lshl_b64 s[84:85], s[84:85], 1
	v_cvt_pk_bf16_f32 v124, v124, v125
	v_cvt_pk_bf16_f32 v125, v126, v127
	v_cvt_pk_bf16_f32 v126, v120, v121
	v_cvt_pk_bf16_f32 v127, v122, v123
	v_cvt_pk_bf16_f32 v112, v112, v113
	v_cvt_pk_bf16_f32 v113, v114, v115
	v_cvt_pk_bf16_f32 v114, v104, v105
	v_cvt_pk_bf16_f32 v115, v106, v107
	v_lshl_add_u64 v[104:105], v[156:157], 0, s[84:85]
	global_store_dwordx4 v[156:157], v[124:127], off nt
	global_store_dwordx4 v[104:105], v[112:115], off nt
	v_mul_lo_u32 v106, s83, v140
	v_mul_lo_u32 v107, s82, v141
	v_mad_u64_u32 v[104:105], s[14:15], s82, v140, 0
	v_add3_u32 v105, v105, v107, v106
	v_lshlrev_b64 v[112:113], 1, v[104:105]
	v_lshl_add_u64 v[104:105], s[68:69], 0, v[112:113]
	v_lshl_add_u64 v[104:105], v[104:105], 0, s[86:87]
	v_lshl_add_u64 v[104:105], v[104:105], 0, s[62:63]
	v_lshl_add_u64 v[114:115], v[104:105], 0, v[136:137]
	v_cvt_pk_bf16_f32 v104, v116, v117
	v_cvt_pk_bf16_f32 v105, v118, v119
	v_cvt_pk_bf16_f32 v106, v108, v109
	v_cvt_pk_bf16_f32 v107, v110, v111
	v_cvt_pk_bf16_f32 v96, v96, v97
	v_cvt_pk_bf16_f32 v97, v98, v99
	v_cvt_pk_bf16_f32 v98, v88, v89
	v_cvt_pk_bf16_f32 v99, v90, v91
	v_lshl_add_u64 v[88:89], v[114:115], 0, s[84:85]
	global_store_dwordx4 v[114:115], v[104:107], off nt
	global_store_dwordx4 v[88:89], v[96:99], off nt
	v_mul_lo_u32 v90, s83, v142
	v_mul_lo_u32 v91, s82, v143
	v_mad_u64_u32 v[88:89], s[14:15], s82, v142, 0
	v_add3_u32 v89, v89, v91, v90
	v_lshlrev_b64 v[96:97], 1, v[88:89]
	v_lshl_add_u64 v[88:89], s[68:69], 0, v[96:97]
	v_lshl_add_u64 v[88:89], v[88:89], 0, s[86:87]
	v_lshl_add_u64 v[88:89], v[88:89], 0, s[62:63]
	v_lshl_add_u64 v[98:99], v[88:89], 0, v[136:137]
	v_cvt_pk_bf16_f32 v88, v100, v101
	v_cvt_pk_bf16_f32 v89, v102, v103
	v_cvt_pk_bf16_f32 v90, v92, v93
	v_cvt_pk_bf16_f32 v91, v94, v95
	v_cvt_pk_bf16_f32 v80, v80, v81
	v_cvt_pk_bf16_f32 v81, v82, v83
	v_cvt_pk_bf16_f32 v82, v72, v73
	v_cvt_pk_bf16_f32 v83, v74, v75
	v_lshl_add_u64 v[72:73], v[98:99], 0, s[84:85]
	global_store_dwordx4 v[98:99], v[88:91], off nt
	global_store_dwordx4 v[72:73], v[80:83], off nt
	v_mul_lo_u32 v74, s83, v144
	v_mul_lo_u32 v75, s82, v145
	v_mad_u64_u32 v[72:73], s[14:15], s82, v144, 0
	v_add3_u32 v73, v73, v75, v74
	v_lshlrev_b64 v[80:81], 1, v[72:73]
	v_lshl_add_u64 v[72:73], s[68:69], 0, v[80:81]
	v_lshl_add_u64 v[72:73], v[72:73], 0, s[86:87]
	v_lshl_add_u64 v[72:73], v[72:73], 0, s[62:63]
	v_lshl_add_u64 v[82:83], v[72:73], 0, v[136:137]
	s_add_u32 s14, s68, 0x800000
	v_cvt_pk_bf16_f32 v72, v84, v85
	v_cvt_pk_bf16_f32 v73, v86, v87
	v_cvt_pk_bf16_f32 v74, v76, v77
	v_cvt_pk_bf16_f32 v75, v78, v79
	v_cvt_pk_bf16_f32 v68, v68, v69
	v_cvt_pk_bf16_f32 v69, v70, v71
	v_cvt_pk_bf16_f32 v70, v64, v65
	v_cvt_pk_bf16_f32 v71, v66, v67
	v_lshl_add_u64 v[64:65], v[82:83], 0, s[84:85]
	s_addc_u32 s15, s69, 0
	global_store_dwordx4 v[82:83], v[72:75], off nt
	global_store_dwordx4 v[64:65], v[68:71], off nt
	v_lshl_add_u64 v[64:65], s[14:15], 0, v[154:155]
	v_lshl_add_u64 v[64:65], v[64:65], 0, s[86:87]
	v_lshl_add_u64 v[64:65], v[64:65], 0, s[62:63]
	v_lshl_add_u64 v[64:65], v[64:65], 0, v[136:137]
	v_cvt_pk_bf16_f32 v60, v60, v61
	v_cvt_pk_bf16_f32 v61, v62, v63
	v_cvt_pk_bf16_f32 v62, v56, v57
	v_cvt_pk_bf16_f32 v63, v58, v59
	v_cvt_pk_bf16_f32 v44, v44, v45
	v_cvt_pk_bf16_f32 v45, v46, v47
	v_cvt_pk_bf16_f32 v46, v40, v41
	v_cvt_pk_bf16_f32 v47, v42, v43
	v_lshl_add_u64 v[40:41], v[64:65], 0, s[84:85]
	global_store_dwordx4 v[64:65], v[60:63], off nt
	global_store_dwordx4 v[40:41], v[44:47], off nt
	v_lshl_add_u64 v[40:41], s[14:15], 0, v[112:113]
	v_lshl_add_u64 v[40:41], v[40:41], 0, s[86:87]
	v_lshl_add_u64 v[40:41], v[40:41], 0, s[62:63]
	v_lshl_add_u64 v[44:45], v[40:41], 0, v[136:137]
	v_cvt_pk_bf16_f32 v40, v52, v53
	v_cvt_pk_bf16_f32 v41, v54, v55
	v_cvt_pk_bf16_f32 v42, v48, v49
	v_cvt_pk_bf16_f32 v43, v50, v51
	v_cvt_pk_bf16_f32 v28, v28, v29
	v_cvt_pk_bf16_f32 v29, v30, v31
	v_cvt_pk_bf16_f32 v30, v24, v25
	v_cvt_pk_bf16_f32 v31, v26, v27
	v_lshl_add_u64 v[24:25], v[44:45], 0, s[84:85]
	global_store_dwordx4 v[44:45], v[40:43], off nt
	global_store_dwordx4 v[24:25], v[28:31], off nt
	v_lshl_add_u64 v[24:25], s[14:15], 0, v[96:97]
	v_lshl_add_u64 v[24:25], v[24:25], 0, s[86:87]
	v_lshl_add_u64 v[24:25], v[24:25], 0, s[62:63]
	v_lshl_add_u64 v[28:29], v[24:25], 0, v[136:137]
	v_cvt_pk_bf16_f32 v24, v36, v37
	v_cvt_pk_bf16_f32 v25, v38, v39
	v_cvt_pk_bf16_f32 v26, v32, v33
	v_cvt_pk_bf16_f32 v27, v34, v35
	v_cvt_pk_bf16_f32 v12, v12, v13
	v_cvt_pk_bf16_f32 v13, v14, v15
	v_cvt_pk_bf16_f32 v14, v8, v9
	v_cvt_pk_bf16_f32 v15, v10, v11
	v_lshl_add_u64 v[8:9], v[28:29], 0, s[84:85]
	global_store_dwordx4 v[28:29], v[24:27], off nt
	global_store_dwordx4 v[8:9], v[12:15], off nt
	v_lshl_add_u64 v[8:9], s[14:15], 0, v[80:81]
	v_lshl_add_u64 v[8:9], v[8:9], 0, s[86:87]
	v_lshl_add_u64 v[8:9], v[8:9], 0, s[62:63]
	v_lshl_add_u64 v[12:13], v[8:9], 0, v[136:137]
	v_cvt_pk_bf16_f32 v8, v20, v21
	v_cvt_pk_bf16_f32 v9, v22, v23
	v_cvt_pk_bf16_f32 v10, v16, v17
	v_cvt_pk_bf16_f32 v11, v18, v19
	v_cvt_pk_bf16_f32 v4, v4, v5
	v_cvt_pk_bf16_f32 v5, v6, v7
	v_cvt_pk_bf16_f32 v6, v0, v1
	v_cvt_pk_bf16_f32 v7, v2, v3
	v_lshl_add_u64 v[0:1], v[12:13], 0, s[84:85]
	s_andn2_b64 vcc, exec, s[70:71]
	s_mov_b64 s[14:15], -1
	global_store_dwordx4 v[12:13], v[8:11], off nt
	global_store_dwordx4 v[0:1], v[4:7], off nt
	s_cbranch_vccnz .LBB0_115
	s_andn2_b64 vcc, exec, s[6:7]
	s_cbranch_vccnz .LBB0_114
	s_barrier
	s_branch .LBB0_114
